# c6: adds early issue of G-tile (c,dt) pairs, s_rs and D-skip LDS reads in ssd pass 3
# speedup vs baseline: 1.0214x; 1.0214x over previous
; __device__ __forceinline__ unsigned pk2(float lo, float hi) { f32x2 v = {lo, hi}; bf16x2_t b = __builtin_convertvector(v, bf16x2_t); return __builtin_bit_cast(unsigned, b); }
; __device__ __forceinline__ float bflo(unsigned u) { return __uint_as_float(u << 16); }
; __device__ __forceinline__ float bfhi(unsigned u) { return __uint_as_float(u & 0xffff0000u); }
; template <int PASS>
; __device__ void ssd_item(const Params& p, int item, int l, unsigned char* smem) {
;     ...
;         const float* s_dt = s_dta + scn * TSUB; const float* s_c = s_cA + scn * TSUB; const float* s_rs = s_rsA + scn * TSUB; const float* s_wl = s_wlA + scn * TSUB;
;         const float stot = s_totA[scn];
;         segtot += stot;
; #pragma unroll
;         for (int i = 0; i < 5; ++i) { const int u = tid + 256 * i, lrow = u / 40, ci = u % 40, lc = ci * 8; const u32x4 o = raw[i];
;             if (ci < 8) { *(u32x4*)(Xs + lrow * 72 + lc) = o; const float wl = s_wl[lrow];
;                 u32x4 o2; o2.x = pk2(bflo(o.x) * wl, bfhi(o.x) * wl); o2.y = pk2(bflo(o.y) * wl, bfhi(o.y) * wl); o2.z = pk2(bflo(o.z) * wl, bfhi(o.z) * wl); o2.w = pk2(bflo(o.w) * wl, bfhi(o.w) * wl);
.Lssd1_join:
	v_lshl_add_u32 v85, s24, 7, v54
	s_mulk_i32 s24, 0xff84
	v_add_u32_e32 v84, s24, v85
	ds_read_b32 v84, v84 offset:54272
	v_lshl_add_u32 v150, v53, 2, v85
	ds_read_b32 v150, v150 offset:50688
	v_lshl_add_u32 v152, v55, 2, v85
	ds_read_b32 v152, v152 offset:50688
	v_lshl_add_u32 v154, v56, 2, v85
	ds_read_b32 v154, v154 offset:50688
	v_lshl_add_u32 v156, v57, 2, v85
	ds_read_b32 v156, v156 offset:50688
	v_lshl_add_u32 v158, v58, 2, v85
	ds_read_b32 v158, v158 offset:50688
	s_waitcnt lgkmcnt(0)
	s_and_saveexec_b64 s[24:25], s[36:37]
	s_xor_b64 s[66:67], exec, s[24:25]
	s_cbranch_execnz .LBB0_747
	s_andn2_saveexec_b64 s[66:67], s[66:67]
	s_cbranch_execnz .LBB0_752

; __device__ __forceinline__ unsigned pk2(float lo, float hi) { f32x2 v = {lo, hi}; bf16x2_t b = __builtin_convertvector(v, bf16x2_t); return __builtin_bit_cast(unsigned, b); }
; __device__ __forceinline__ float bflo(unsigned u) { return __uint_as_float(u << 16); }
; __device__ __forceinline__ float bfhi(unsigned u) { return __uint_as_float(u & 0xffff0000u); }
; template <int PASS>
; __device__ void ssd_item(const Params& p, int item, int l, unsigned char* smem) {
;     ...
;         for (int i = 0; i < 5; ++i) { const int u = tid + 256 * i, lrow = u / 40, ci = u % 40, lc = ci * 8; const u32x4 o = raw[i];
;             if (ci < 8) { *(u32x4*)(Xs + lrow * 72 + lc) = o; const float wl = s_wl[lrow];
;                 u32x4 o2; o2.x = pk2(bflo(o.x) * wl, bfhi(o.x) * wl); o2.y = pk2(bflo(o.y) * wl, bfhi(o.y) * wl); o2.z = pk2(bflo(o.z) * wl, bfhi(o.z) * wl); o2.w = pk2(bflo(o.w) * wl, bfhi(o.w) * wl);
;                 *(u32x4*)(Xws + lrow * 72 + lc) = o2; }
.LBB0_752:
	ds_write_b128 v68, v[48:51] offset:17408
	v_lshlrev_b32_e32 v88, 16, v48
	v_and_b32_e32 v89, 0xffff0000, v48
	v_pk_mul_f32 v[88:89], v[150:151], v[88:89] op_sel_hi:[0,1]
	v_cvt_pk_bf16_f32 v48, v88, v89
	v_lshlrev_b32_e32 v88, 16, v49
	v_and_b32_e32 v89, 0xffff0000, v49
	v_pk_mul_f32 v[88:89], v[150:151], v[88:89] op_sel_hi:[0,1]
	v_cvt_pk_bf16_f32 v49, v88, v89
	v_lshlrev_b32_e32 v88, 16, v50
	v_and_b32_e32 v89, 0xffff0000, v50
	v_pk_mul_f32 v[88:89], v[150:151], v[88:89] op_sel_hi:[0,1]
	v_cvt_pk_bf16_f32 v50, v88, v89
	v_lshlrev_b32_e32 v88, 16, v51
	v_and_b32_e32 v89, 0xffff0000, v51
	v_pk_mul_f32 v[150:151], v[150:151], v[88:89] op_sel_hi:[0,1]
	v_cvt_pk_bf16_f32 v51, v150, v151
	ds_write_b128 v68, v[48:51] offset:22016
	s_or_b64 exec, exec, s[66:67]
	s_and_saveexec_b64 s[24:25], s[38:39]
	s_xor_b64 s[66:67], exec, s[24:25]
	s_cbranch_execz .LBB0_740

; __device__ __forceinline__ unsigned pk2(float lo, float hi) { f32x2 v = {lo, hi}; bf16x2_t b = __builtin_convertvector(v, bf16x2_t); return __builtin_bit_cast(unsigned, b); }
; __device__ __forceinline__ float bflo(unsigned u) { return __uint_as_float(u << 16); }
; __device__ __forceinline__ float bfhi(unsigned u) { return __uint_as_float(u & 0xffff0000u); }
; template <int PASS>
; __device__ void ssd_item(const Params& p, int item, int l, unsigned char* smem) {
;     ...
;         for (int i = 0; i < 5; ++i) { const int u = tid + 256 * i, lrow = u / 40, ci = u % 40, lc = ci * 8; const u32x4 o = raw[i];
;             if (ci < 8) { *(u32x4*)(Xs + lrow * 72 + lc) = o; const float wl = s_wl[lrow];
;                 u32x4 o2; o2.x = pk2(bflo(o.x) * wl, bfhi(o.x) * wl); o2.y = pk2(bflo(o.y) * wl, bfhi(o.y) * wl); o2.z = pk2(bflo(o.z) * wl, bfhi(o.z) * wl); o2.w = pk2(bflo(o.w) * wl, bfhi(o.w) * wl);
;                 *(u32x4*)(Xws + lrow * 72 + lc) = o2; }
.LBB0_758:
	ds_write_b128 v71, v[44:47] offset:17408
	v_lshlrev_b32_e32 v50, 16, v44
	v_and_b32_e32 v51, 0xffff0000, v44
	v_pk_mul_f32 v[50:51], v[152:153], v[50:51] op_sel_hi:[0,1]
	v_cvt_pk_bf16_f32 v44, v50, v51
	v_lshlrev_b32_e32 v50, 16, v45
	v_and_b32_e32 v51, 0xffff0000, v45
	v_pk_mul_f32 v[50:51], v[152:153], v[50:51] op_sel_hi:[0,1]
	v_cvt_pk_bf16_f32 v45, v50, v51
	v_lshlrev_b32_e32 v50, 16, v46
	v_and_b32_e32 v51, 0xffff0000, v46
	v_pk_mul_f32 v[50:51], v[152:153], v[50:51] op_sel_hi:[0,1]
	v_cvt_pk_bf16_f32 v46, v50, v51
	v_lshlrev_b32_e32 v50, 16, v47
	v_and_b32_e32 v51, 0xffff0000, v47
	v_pk_mul_f32 v[152:153], v[152:153], v[50:51] op_sel_hi:[0,1]
	v_cvt_pk_bf16_f32 v47, v152, v153
	ds_write_b128 v71, v[44:47] offset:22016
	s_or_b64 exec, exec, s[66:67]
	s_and_saveexec_b64 s[24:25], s[40:41]
	s_xor_b64 s[66:67], exec, s[24:25]
	s_cbranch_execz .LBB0_742

; __device__ __forceinline__ unsigned pk2(float lo, float hi) { f32x2 v = {lo, hi}; bf16x2_t b = __builtin_convertvector(v, bf16x2_t); return __builtin_bit_cast(unsigned, b); }
; __device__ __forceinline__ float bflo(unsigned u) { return __uint_as_float(u << 16); }
; __device__ __forceinline__ float bfhi(unsigned u) { return __uint_as_float(u & 0xffff0000u); }
; template <int PASS>
; __device__ void ssd_item(const Params& p, int item, int l, unsigned char* smem) {
;     ...
;         for (int i = 0; i < 5; ++i) { const int u = tid + 256 * i, lrow = u / 40, ci = u % 40, lc = ci * 8; const u32x4 o = raw[i];
;             if (ci < 8) { *(u32x4*)(Xs + lrow * 72 + lc) = o; const float wl = s_wl[lrow];
;                 u32x4 o2; o2.x = pk2(bflo(o.x) * wl, bfhi(o.x) * wl); o2.y = pk2(bflo(o.y) * wl, bfhi(o.y) * wl); o2.z = pk2(bflo(o.z) * wl, bfhi(o.z) * wl); o2.w = pk2(bflo(o.w) * wl, bfhi(o.w) * wl);
;                 *(u32x4*)(Xws + lrow * 72 + lc) = o2; }
.LBB0_764:
	ds_write_b128 v74, v[40:43] offset:17408
	v_lshlrev_b32_e32 v46, 16, v40
	v_and_b32_e32 v47, 0xffff0000, v40
	v_pk_mul_f32 v[46:47], v[154:155], v[46:47] op_sel_hi:[0,1]
	v_cvt_pk_bf16_f32 v40, v46, v47
	v_lshlrev_b32_e32 v46, 16, v41
	v_and_b32_e32 v47, 0xffff0000, v41
	v_pk_mul_f32 v[46:47], v[154:155], v[46:47] op_sel_hi:[0,1]
	v_cvt_pk_bf16_f32 v41, v46, v47
	v_lshlrev_b32_e32 v46, 16, v42
	v_and_b32_e32 v47, 0xffff0000, v42
	v_pk_mul_f32 v[46:47], v[154:155], v[46:47] op_sel_hi:[0,1]
	v_cvt_pk_bf16_f32 v42, v46, v47
	v_lshlrev_b32_e32 v46, 16, v43
	v_and_b32_e32 v47, 0xffff0000, v43
	v_pk_mul_f32 v[154:155], v[154:155], v[46:47] op_sel_hi:[0,1]
	v_cvt_pk_bf16_f32 v43, v154, v155
	ds_write_b128 v74, v[40:43] offset:22016
	s_or_b64 exec, exec, s[66:67]
	s_and_saveexec_b64 s[24:25], s[42:43]
	s_xor_b64 s[66:67], exec, s[24:25]
	s_cbranch_execz .LBB0_744

; __device__ __forceinline__ unsigned pk2(float lo, float hi) { f32x2 v = {lo, hi}; bf16x2_t b = __builtin_convertvector(v, bf16x2_t); return __builtin_bit_cast(unsigned, b); }
; __device__ __forceinline__ float bflo(unsigned u) { return __uint_as_float(u << 16); }
; __device__ __forceinline__ float bfhi(unsigned u) { return __uint_as_float(u & 0xffff0000u); }
; template <int PASS>
; __device__ void ssd_item(const Params& p, int item, int l, unsigned char* smem) {
;     ...
;         for (int i = 0; i < 5; ++i) { const int u = tid + 256 * i, lrow = u / 40, ci = u % 40, lc = ci * 8; const u32x4 o = raw[i];
;             if (ci < 8) { *(u32x4*)(Xs + lrow * 72 + lc) = o; const float wl = s_wl[lrow];
;                 u32x4 o2; o2.x = pk2(bflo(o.x) * wl, bfhi(o.x) * wl); o2.y = pk2(bflo(o.y) * wl, bfhi(o.y) * wl); o2.z = pk2(bflo(o.z) * wl, bfhi(o.z) * wl); o2.w = pk2(bflo(o.w) * wl, bfhi(o.w) * wl);
;                 *(u32x4*)(Xws + lrow * 72 + lc) = o2; }
.LBB0_770:
	ds_write_b128 v77, v[36:39] offset:17408
	v_lshlrev_b32_e32 v42, 16, v36
	v_and_b32_e32 v43, 0xffff0000, v36
	v_pk_mul_f32 v[42:43], v[156:157], v[42:43] op_sel_hi:[0,1]
	v_cvt_pk_bf16_f32 v36, v42, v43
	v_lshlrev_b32_e32 v42, 16, v37
	v_and_b32_e32 v43, 0xffff0000, v37
	v_pk_mul_f32 v[42:43], v[156:157], v[42:43] op_sel_hi:[0,1]
	v_cvt_pk_bf16_f32 v37, v42, v43
	v_lshlrev_b32_e32 v42, 16, v38
	v_and_b32_e32 v43, 0xffff0000, v38
	v_pk_mul_f32 v[42:43], v[156:157], v[42:43] op_sel_hi:[0,1]
	v_cvt_pk_bf16_f32 v38, v42, v43
	v_lshlrev_b32_e32 v42, 16, v39
	v_and_b32_e32 v43, 0xffff0000, v39
	v_pk_mul_f32 v[156:157], v[156:157], v[42:43] op_sel_hi:[0,1]
	v_cvt_pk_bf16_f32 v39, v156, v157
	ds_write_b128 v77, v[36:39] offset:22016
	s_or_b64 exec, exec, s[66:67]
	s_and_saveexec_b64 s[24:25], s[44:45]
	s_xor_b64 s[66:67], exec, s[24:25]
	s_cbranch_execz .LBB0_746

; __device__ __forceinline__ unsigned pk2(float lo, float hi) { f32x2 v = {lo, hi}; bf16x2_t b = __builtin_convertvector(v, bf16x2_t); return __builtin_bit_cast(unsigned, b); }
; __device__ __forceinline__ float bflo(unsigned u) { return __uint_as_float(u << 16); }
; __device__ __forceinline__ float bfhi(unsigned u) { return __uint_as_float(u & 0xffff0000u); }
; template <int PASS>
; __device__ void ssd_item(const Params& p, int item, int l, unsigned char* smem) {
;     ...
;         for (int i = 0; i < 5; ++i) { const int u = tid + 256 * i, lrow = u / 40, ci = u % 40, lc = ci * 8; const u32x4 o = raw[i];
;             if (ci < 8) { *(u32x4*)(Xs + lrow * 72 + lc) = o; const float wl = s_wl[lrow];
;                 u32x4 o2; o2.x = pk2(bflo(o.x) * wl, bfhi(o.x) * wl); o2.y = pk2(bflo(o.y) * wl, bfhi(o.y) * wl); o2.z = pk2(bflo(o.z) * wl, bfhi(o.z) * wl); o2.w = pk2(bflo(o.w) * wl, bfhi(o.w) * wl);
;                 *(u32x4*)(Xws + lrow * 72 + lc) = o2; }
.LBB0_776:
	ds_write_b128 v80, v[32:35] offset:17408
	v_lshlrev_b32_e32 v38, 16, v32
	v_and_b32_e32 v39, 0xffff0000, v32
	v_pk_mul_f32 v[38:39], v[158:159], v[38:39] op_sel_hi:[0,1]
	v_cvt_pk_bf16_f32 v32, v38, v39
	v_lshlrev_b32_e32 v38, 16, v33
	v_and_b32_e32 v39, 0xffff0000, v33
	v_pk_mul_f32 v[38:39], v[158:159], v[38:39] op_sel_hi:[0,1]
	v_cvt_pk_bf16_f32 v33, v38, v39
	v_lshlrev_b32_e32 v38, 16, v34
	v_and_b32_e32 v39, 0xffff0000, v34
	v_pk_mul_f32 v[38:39], v[158:159], v[38:39] op_sel_hi:[0,1]
	v_cvt_pk_bf16_f32 v34, v38, v39
	v_lshlrev_b32_e32 v38, 16, v35
	v_and_b32_e32 v39, 0xffff0000, v35
	v_pk_mul_f32 v[158:159], v[158:159], v[38:39] op_sel_hi:[0,1]
	v_cvt_pk_bf16_f32 v35, v158, v159
	ds_write_b128 v80, v[32:35] offset:22016
	s_branch .LBB0_736

; template <int PASS>
; __device__ void ssd_item(const Params& p, int item, int l, unsigned char* smem) {
;     ...
;             for (int e = NSEG - 1; e > seg; --e) { const float dc = __expf(SEGT[ibase + e]); const f32x4* src = (const f32x4*)(ST + (size_t)(ibase + e) * 8192);
; #pragma unroll
;                 for (int nt = 0; nt < 8; ++nt) S[nt] = S[nt] * dc + src[(w * 8 + nt) * 64 + lane]; }
.LBB0_860:
	s_add_u32 s26, s92, s22
	s_addc_u32 s27, s93, s23
	global_load_dword v162, v81, s[26:27]
	s_mov_b32 s25, 0x1b078000
	s_add_i32 s24, s24, -1
	s_add_u32 s22, s22, -4
	s_movk_i32 s26, 0x8000
	s_addc_u32 s23, s23, -1
	s_mov_b32 s27, -1
	s_cmp_gt_u32 s24, s12
	v_lshl_add_u64 v[38:39], s[92:93], 0, v[34:35]
	v_add_co_u32_e32 v44, vcc, s25, v38
	s_mov_b32 s25, 0x1b079000
	s_nop 0
	v_addc_co_u32_e32 v45, vcc, 0, v39, vcc
	v_add_co_u32_e32 v46, vcc, s25, v38
	v_lshl_add_u64 v[34:35], v[34:35], 0, s[26:27]
	s_nop 0
	v_addc_co_u32_e32 v47, vcc, 0, v39, vcc
	global_load_dwordx4 v[120:123], v[46:47], off offset:-4096
	global_load_dwordx4 v[124:127], v[44:45], off offset:1024
	global_load_dwordx4 v[128:131], v[44:45], off offset:2048
	global_load_dwordx4 v[132:135], v[44:45], off offset:3072
	global_load_dwordx4 v[136:139], v[46:47], off
	global_load_dwordx4 v[140:143], v[46:47], off offset:1024
	global_load_dwordx4 v[144:147], v[46:47], off offset:2048
	global_load_dwordx4 v[148:151], v[46:47], off offset:3072
	s_waitcnt vmcnt(8)
	v_mul_f32_e32 v162, 0x3fb8aa3b, v162
	v_exp_f32_e32 v42, v162
	s_waitcnt vmcnt(0)
	v_pk_fma_f32 v[2:3], v[2:3], v[42:43], v[122:123] op_sel_hi:[1,0,1]
	v_pk_fma_f32 v[0:1], v[0:1], v[42:43], v[120:121] op_sel_hi:[1,0,1]
	v_pk_fma_f32 v[6:7], v[6:7], v[42:43], v[126:127] op_sel_hi:[1,0,1]
	v_pk_fma_f32 v[4:5], v[4:5], v[42:43], v[124:125] op_sel_hi:[1,0,1]
	v_pk_fma_f32 v[10:11], v[10:11], v[42:43], v[130:131] op_sel_hi:[1,0,1]
	v_pk_fma_f32 v[8:9], v[8:9], v[42:43], v[128:129] op_sel_hi:[1,0,1]
	v_pk_fma_f32 v[14:15], v[14:15], v[42:43], v[134:135] op_sel_hi:[1,0,1]
	v_pk_fma_f32 v[12:13], v[12:13], v[42:43], v[132:133] op_sel_hi:[1,0,1]
	v_pk_fma_f32 v[18:19], v[18:19], v[42:43], v[138:139] op_sel_hi:[1,0,1]
	v_pk_fma_f32 v[16:17], v[16:17], v[42:43], v[136:137] op_sel_hi:[1,0,1]
	v_pk_fma_f32 v[22:23], v[22:23], v[42:43], v[142:143] op_sel_hi:[1,0,1]
	v_pk_fma_f32 v[20:21], v[20:21], v[42:43], v[140:141] op_sel_hi:[1,0,1]
	v_pk_fma_f32 v[26:27], v[26:27], v[42:43], v[146:147] op_sel_hi:[1,0,1]
	v_pk_fma_f32 v[24:25], v[24:25], v[42:43], v[144:145] op_sel_hi:[1,0,1]
	v_pk_fma_f32 v[30:31], v[30:31], v[42:43], v[150:151] op_sel_hi:[1,0,1]
	v_pk_fma_f32 v[28:29], v[28:29], v[42:43], v[148:149] op_sel_hi:[1,0,1]
	s_cbranch_scc1 .LBB0_860
	s_mov_b64 s[42:43], 0

; template <int PASS>
; __device__ void ssd_item(const Params& p, int item, int l, unsigned char* smem) {
;     ...
;             for (int e = 0; e < seg; ++e) { const float dc = __expf(SEGT[ibase + e]); const f32x4* src = (const f32x4*)(ST + (size_t)(ibase + e) * 8192);
; #pragma unroll
;                 for (int nt = 0; nt < 8; ++nt) S[nt] = S[nt] * dc + src[(w * 8 + nt) * 64 + lane]; }
.LBB0_865:
	s_add_u32 s26, s92, s23
	s_addc_u32 s27, s93, s24
	global_load_dword v162, v81, s[26:27]
	s_mov_b32 s25, 0x1b000000
	s_add_i32 s22, s22, -1
	s_add_u32 s23, s23, 4
	s_addc_u32 s24, s24, 0
	s_cmp_eq_u32 s22, 0
	v_lshl_add_u64 v[38:39], s[92:93], 0, v[34:35]
	v_add_co_u32_e32 v44, vcc, s25, v38
	s_mov_b32 s25, 0x1b001000
	s_nop 0
	v_addc_co_u32_e32 v45, vcc, 0, v39, vcc
	v_add_co_u32_e32 v46, vcc, s25, v38
	v_lshl_add_u64 v[34:35], v[34:35], 0, s[14:15]
	s_nop 0
	v_addc_co_u32_e32 v47, vcc, 0, v39, vcc
	global_load_dwordx4 v[120:123], v[46:47], off offset:-4096
	global_load_dwordx4 v[124:127], v[44:45], off offset:1024
	global_load_dwordx4 v[128:131], v[44:45], off offset:2048
	global_load_dwordx4 v[132:135], v[44:45], off offset:3072
	global_load_dwordx4 v[136:139], v[46:47], off
	global_load_dwordx4 v[140:143], v[46:47], off offset:1024
	global_load_dwordx4 v[144:147], v[46:47], off offset:2048
	global_load_dwordx4 v[148:151], v[46:47], off offset:3072
	s_waitcnt vmcnt(8)
	v_mul_f32_e32 v162, 0x3fb8aa3b, v162
	v_exp_f32_e32 v42, v162
	s_waitcnt vmcnt(0)
	v_pk_fma_f32 v[2:3], v[2:3], v[42:43], v[122:123] op_sel_hi:[1,0,1]
	v_pk_fma_f32 v[0:1], v[0:1], v[42:43], v[120:121] op_sel_hi:[1,0,1]
	v_pk_fma_f32 v[6:7], v[6:7], v[42:43], v[126:127] op_sel_hi:[1,0,1]
	v_pk_fma_f32 v[4:5], v[4:5], v[42:43], v[124:125] op_sel_hi:[1,0,1]
	v_pk_fma_f32 v[10:11], v[10:11], v[42:43], v[130:131] op_sel_hi:[1,0,1]
	v_pk_fma_f32 v[8:9], v[8:9], v[42:43], v[128:129] op_sel_hi:[1,0,1]
	v_pk_fma_f32 v[14:15], v[14:15], v[42:43], v[134:135] op_sel_hi:[1,0,1]
	v_pk_fma_f32 v[12:13], v[12:13], v[42:43], v[132:133] op_sel_hi:[1,0,1]
	v_pk_fma_f32 v[18:19], v[18:19], v[42:43], v[138:139] op_sel_hi:[1,0,1]
	v_pk_fma_f32 v[16:17], v[16:17], v[42:43], v[136:137] op_sel_hi:[1,0,1]
	v_pk_fma_f32 v[22:23], v[22:23], v[42:43], v[142:143] op_sel_hi:[1,0,1]
	v_pk_fma_f32 v[20:21], v[20:21], v[42:43], v[140:141] op_sel_hi:[1,0,1]
	v_pk_fma_f32 v[26:27], v[26:27], v[42:43], v[146:147] op_sel_hi:[1,0,1]
	v_pk_fma_f32 v[24:25], v[24:25], v[42:43], v[144:145] op_sel_hi:[1,0,1]
	v_pk_fma_f32 v[30:31], v[30:31], v[42:43], v[150:151] op_sel_hi:[1,0,1]
	v_pk_fma_f32 v[28:29], v[28:29], v[42:43], v[148:149] op_sel_hi:[1,0,1]
	s_cbranch_scc0 .LBB0_865
	s_branch .LBB0_868

; __device__ __forceinline__ unsigned pk2(float lo, float hi) { f32x2 v = {lo, hi}; bf16x2_t b = __builtin_convertvector(v, bf16x2_t); return __builtin_bit_cast(unsigned, b); }
; __device__ __forceinline__ float bflo(unsigned u) { return __uint_as_float(u << 16); }
; __device__ __forceinline__ float bfhi(unsigned u) { return __uint_as_float(u & 0xffff0000u); }
; template <int PASS>
; __device__ void ssd_item(const Params& p, int item, int l, unsigned char* smem) {
;     ...
;         const float* s_dt = s_dta + scn * TSUB; const float* s_c = s_cA + scn * TSUB; const float* s_rs = s_rsA + scn * TSUB; const float* s_wl = s_wlA + scn * TSUB;
;         const float stot = s_totA[scn];
;         segtot += stot;
; #pragma unroll
;         for (int i = 0; i < 5; ++i) { const int u = tid + 256 * i, lrow = u / 40, ci = u % 40, lc = ci * 8; const u32x4 o = raw[i];
;             if (ci < 8) { *(u32x4*)(Xs + lrow * 72 + lc) = o; const float wl = s_wl[lrow];
;                 u32x4 o2; o2.x = pk2(bflo(o.x) * wl, bfhi(o.x) * wl); o2.y = pk2(bflo(o.y) * wl, bfhi(o.y) * wl); o2.z = pk2(bflo(o.z) * wl, bfhi(o.z) * wl); o2.w = pk2(bflo(o.w) * wl, bfhi(o.w) * wl);
.Lssd3_join:
	v_lshl_add_u32 v96, s22, 7, v52
	s_mul_i32 s23, s22, 0xffffff84
	v_add_u32_e32 v97, s23, v96
	ds_read_b32 v95, v97 offset:54272
	v_lshl_add_u32 v164, v66, 2, v96
	ds_read_b32 v164, v164 offset:50688
	v_lshl_add_u32 v166, v62, 2, v96
	ds_read_b32 v166, v166 offset:50688
	v_lshl_add_u32 v168, v63, 2, v96
	ds_read_b32 v168, v168 offset:50688
	v_lshl_add_u32 v170, v64, 2, v96
	ds_read_b32 v170, v170 offset:50688
	v_lshl_add_u32 v172, v65, 2, v96
	ds_read_b32 v172, v172 offset:50688
	s_waitcnt lgkmcnt(0)
	s_and_saveexec_b64 s[24:25], s[38:39]
	s_xor_b64 s[66:67], exec, s[24:25]
	s_cbranch_execnz .LBB0_934
	s_andn2_saveexec_b64 s[66:67], s[66:67]
	s_cbranch_execnz .LBB0_939

; __device__ __forceinline__ unsigned pk2(float lo, float hi) { f32x2 v = {lo, hi}; bf16x2_t b = __builtin_convertvector(v, bf16x2_t); return __builtin_bit_cast(unsigned, b); }
; __device__ __forceinline__ float bflo(unsigned u) { return __uint_as_float(u << 16); }
; __device__ __forceinline__ float bfhi(unsigned u) { return __uint_as_float(u & 0xffff0000u); }
; template <int PASS>
; __device__ void ssd_item(const Params& p, int item, int l, unsigned char* smem) {
;     ...
;         for (int i = 0; i < 5; ++i) { const int u = tid + 256 * i, lrow = u / 40, ci = u % 40, lc = ci * 8; const u32x4 o = raw[i];
;             if (ci < 8) { *(u32x4*)(Xs + lrow * 72 + lc) = o; const float wl = s_wl[lrow];
;                 u32x4 o2; o2.x = pk2(bflo(o.x) * wl, bfhi(o.x) * wl); o2.y = pk2(bflo(o.y) * wl, bfhi(o.y) * wl); o2.z = pk2(bflo(o.z) * wl, bfhi(o.z) * wl); o2.w = pk2(bflo(o.w) * wl, bfhi(o.w) * wl);
;                 *(u32x4*)(Xws + lrow * 72 + lc) = o2; }
;     ...
;                 const int ii = 16 * it + idx; const float ci_ = s_c[ii];
;                 f32x4 gv;
; #pragma unroll
;                 for (int rg = 0; rg < 4; ++rg) {
;                     const int jj = 16 * jt + 4 * kq + rg;
;                     const bool ok = dir ? (jj >= ii) : (jj <= ii);
;                     const float e = __expf(ci_ - s_c[jj]) * s_dt[jj];
;                     gv[rg] = ok ? cb[rg] * e : 0.f;
;                 }
.LBB0_924:
	ds_write_b128 v92, v[32:35] offset:17408
	v_lshlrev_b32_e32 v38, 16, v32
	v_and_b32_e32 v39, 0xffff0000, v32
	v_pk_mul_f32 v[38:39], v[164:165], v[38:39] op_sel_hi:[0,1]
	v_cvt_pk_bf16_f32 v32, v38, v39
	v_lshlrev_b32_e32 v38, 16, v33
	v_and_b32_e32 v39, 0xffff0000, v33
	v_pk_mul_f32 v[38:39], v[164:165], v[38:39] op_sel_hi:[0,1]
	v_cvt_pk_bf16_f32 v33, v38, v39
	v_lshlrev_b32_e32 v38, 16, v34
	v_and_b32_e32 v39, 0xffff0000, v34
	v_pk_mul_f32 v[38:39], v[164:165], v[38:39] op_sel_hi:[0,1]
	v_cvt_pk_bf16_f32 v34, v38, v39
	v_lshlrev_b32_e32 v38, 16, v35
	v_and_b32_e32 v39, 0xffff0000, v35
	v_pk_mul_f32 v[164:165], v[164:165], v[38:39] op_sel_hi:[0,1]
	v_cvt_pk_bf16_f32 v35, v164, v165
	ds_write_b128 v92, v[32:35] offset:22016
.LBB0_925:
	s_or_b64 exec, exec, s[66:67]
	s_waitcnt lgkmcnt(0)
	s_barrier
	ds_read_b128 v[32:35], v72
	ds_read_b128 v[36:39], v58 offset:8704
	ds_read_b128 v[42:45], v72 offset:64
	ds_read_b128 v[46:49], v58 offset:8768
	ds_read_b128 v[98:101], v72 offset:128
	ds_read_b128 v[102:105], v58 offset:8832
	ds_read_b128 v[106:109], v72 offset:192
	ds_read_b128 v[110:113], v58 offset:8896
	s_mulk_i32 s22, 0x7c
	v_add_u32_e32 v40, s22, v97
	s_waitcnt lgkmcnt(6)
	v_mfma_f32_16x16x32_bf16 v[32:35], v[32:35], v[36:39], 0
	s_waitcnt lgkmcnt(4)
	v_mfma_f32_16x16x32_bf16 v[32:35], v[42:45], v[46:49], v[32:35]
	s_waitcnt lgkmcnt(2)
	v_mfma_f32_16x16x32_bf16 v[32:35], v[98:101], v[102:105], v[32:35]
	s_waitcnt lgkmcnt(0)
	v_mfma_f32_16x16x32_bf16 v[32:35], v[106:109], v[110:113], v[32:35]
	v_lshl_add_u32 v36, v73, 2, v96
	ds_read_b32 v37, v36 offset:46592
	v_mov_b32_e32 v36, 0
	v_lshl_add_u32 v39, v59, 2, v40
	v_mov_b32_e32 v38, 0
	ds_read2st64_b32 v[174:175], v39 offset0:182 offset1:216
	v_add_u32_e32 v184, 4, v39
	ds_read2st64_b32 v[176:177], v184 offset0:182 offset1:216
	v_add_u32_e32 v184, 8, v39
	ds_read2st64_b32 v[180:181], v184 offset0:182 offset1:216
	v_add_u32_e32 v184, 12, v39
	ds_read2st64_b32 v[182:183], v184 offset0:182 offset1:216
	s_waitcnt lgkmcnt(0)
	s_and_saveexec_b64 s[66:67], s[58:59]
	s_cbranch_execnz .LBB0_963
	s_or_b64 exec, exec, s[66:67]
	v_mov_b32_e32 v32, 0
	s_and_saveexec_b64 s[66:67], s[60:61]
	s_cbranch_execnz .LBB0_964

; template <int PASS>
; __device__ void ssd_item(const Params& p, int item, int l, unsigned char* smem) {
;     ...
;                     const int jj = 16 * jt + 4 * kq + rg;
;                     const bool ok = dir ? (jj >= ii) : (jj <= ii);
;                     const float e = __expf(ci_ - s_c[jj]) * s_dt[jj];
;                     gv[rg] = ok ? cb[rg] * e : 0.f;
.LBB0_929:
	v_sub_f32_e32 v33, v37, v182
	v_mul_f32_e32 v33, 0x3fb8aa3b, v33
	v_exp_f32_e32 v33, v33
	s_nop 0
	v_mul_f32_e32 v33, v183, v33
	v_mul_f32_e32 v33, v35, v33

; __device__ __forceinline__ float bflo(unsigned u) { return __uint_as_float(u << 16); }
; __device__ __forceinline__ float bfhi(unsigned u) { return __uint_as_float(u & 0xffff0000u); }
; __device__ __forceinline__ void st4bf(bf16_t* dst, f32x4 v) { u32x2 pk; pk.x = pk2(v.x, v.y); pk.y = pk2(v.z, v.w); *(u32x2*)dst = pk; }
; template <int PASS>
; __device__ void ssd_item(const Params& p, int item, int l, unsigned char* smem) {
;     ...
;                 const int ii = 16 * it2 + idx;
;                 const bf16x8 gf = *(const bf16x8*)(Gs + ii * 40 + 8 * kq);
;                 f32x4 yd = (f32x4){0.f, 0.f, 0.f, 0.f}, yo = (f32x4){0.f, 0.f, 0.f, 0.f};
;                 bf16x8 sf[4], cf[4];
; #pragma unroll
;                 for (int ks = 0; ks < 4; ++ks) { sf[ks] = *(const bf16x8*)(Sb + (16 * w + idx) * 136 + ks * 32 + kq * 8); cf[ks] = *(const bf16x8*)(Cs + ii * 136 + ks * 32 + kq * 8); }
;                 __builtin_amdgcn_sched_barrier(0);
;                 yd = __builtin_amdgcn_mfma_f32_16x16x32_bf16(xf, gf, yd, 0, 0, 0);
; #pragma unroll
;                 for (int ks = 0; ks < 4; ++ks) yo = __builtin_amdgcn_mfma_f32_16x16x32_bf16(sf[ks], cf[ks], yo, 0, 0, 0);
;                 __builtin_amdgcn_sched_barrier(0);
;                 f32x4 y = yd + yo * s_rs[ii];
;                 if (dir == 0) { const u32x2 xv = *(const u32x2*)(Xs + ii * 72 + 16 * w + 4 * kq);
;                     y.x += Dh * bflo(xv.x); y.y += Dh * bfhi(xv.x); y.z += Dh * bflo(xv.y); y.w += Dh * bfhi(xv.y); }
;                 st4bf(Y + (tokb + t0 + ii) * 512 + h * 64 + 16 * w + 4 * kq, y);
.LBB0_932:
	v_or_b32_e32 v41, s23, v53
	v_mad_u32_u24 v36, v41, s1, v56
	v_mad_u32_u24 v50, v41, s0, v56
	v_lshl_add_u32 v185, v41, 2, v40
	ds_read_b32 v186, v185 offset:48640
	v_mad_u32_u24 v188, v41, s3, v76
	ds_read_b64 v[188:189], v188 offset:17408
	ds_read_b128 v[36:39], v36 offset:26624
	ds_read_b128 v[42:45], v50 offset:8704
	ds_read_b128 v[46:49], v75 offset:29184
	ds_read_b128 v[96:99], v75 offset:29248
	ds_read_b128 v[100:103], v50 offset:8768
	ds_read_b128 v[104:107], v50 offset:8832
	ds_read_b128 v[108:111], v75 offset:29312
	ds_read_b128 v[112:115], v75 offset:29376
	ds_read_b128 v[116:119], v50 offset:8896
	s_waitcnt lgkmcnt(6)
	v_mfma_f32_16x16x32_bf16 v[42:45], v[46:49], v[42:45], 0
	s_waitcnt lgkmcnt(4)
	v_mfma_f32_16x16x32_bf16 v[42:45], v[96:99], v[100:103], v[42:45]
	s_waitcnt lgkmcnt(2)
	v_mfma_f32_16x16x32_bf16 v[42:45], v[108:111], v[104:107], v[42:45]
	s_waitcnt lgkmcnt(0)
	v_mfma_f32_16x16x32_bf16 v[42:45], v[112:115], v[116:119], v[42:45]
	v_mfma_f32_16x16x32_bf16 v[46:49], v[32:35], v[36:39], 0
	s_nop 1
	s_andn2_b64 vcc, exec, s[36:37]
	s_waitcnt lgkmcnt(0)
	s_nop 3
	v_pk_fma_f32 v[36:37], v[44:45], v[186:187], v[48:49] op_sel_hi:[1,0,1]
	v_pk_fma_f32 v[38:39], v[42:43], v[186:187], v[46:47] op_sel_hi:[1,0,1]
	s_cbranch_vccnz .LBB0_931
	v_lshlrev_b32_e32 v44, 16, v188
	v_and_b32_e32 v45, 0xffff0000, v188
	v_lshlrev_b32_e32 v42, 16, v189
	v_and_b32_e32 v43, 0xffff0000, v189
	v_pk_fma_f32 v[38:39], v[54:55], v[44:45], v[38:39]
	v_pk_fma_f32 v[36:37], v[54:55], v[42:43], v[36:37]
	s_branch .LBB0_931

; __device__ __forceinline__ unsigned pk2(float lo, float hi) { f32x2 v = {lo, hi}; bf16x2_t b = __builtin_convertvector(v, bf16x2_t); return __builtin_bit_cast(unsigned, b); }
; __device__ __forceinline__ float bflo(unsigned u) { return __uint_as_float(u << 16); }
; __device__ __forceinline__ float bfhi(unsigned u) { return __uint_as_float(u & 0xffff0000u); }
; template <int PASS>
; __device__ void ssd_item(const Params& p, int item, int l, unsigned char* smem) {
;     ...
;         for (int i = 0; i < 5; ++i) { const int u = tid + 256 * i, lrow = u / 40, ci = u % 40, lc = ci * 8; const u32x4 o = raw[i];
;             if (ci < 8) { *(u32x4*)(Xs + lrow * 72 + lc) = o; const float wl = s_wl[lrow];
;                 u32x4 o2; o2.x = pk2(bflo(o.x) * wl, bfhi(o.x) * wl); o2.y = pk2(bflo(o.y) * wl, bfhi(o.y) * wl); o2.z = pk2(bflo(o.z) * wl, bfhi(o.z) * wl); o2.w = pk2(bflo(o.w) * wl, bfhi(o.w) * wl);
;                 *(u32x4*)(Xws + lrow * 72 + lc) = o2; }
.LBB0_939:
	ds_write_b128 v79, v[48:51] offset:17408
	v_lshlrev_b32_e32 v100, 16, v48
	v_and_b32_e32 v101, 0xffff0000, v48
	v_pk_mul_f32 v[100:101], v[166:167], v[100:101] op_sel_hi:[0,1]
	v_cvt_pk_bf16_f32 v48, v100, v101
	v_lshlrev_b32_e32 v100, 16, v49
	v_and_b32_e32 v101, 0xffff0000, v49
	v_pk_mul_f32 v[100:101], v[166:167], v[100:101] op_sel_hi:[0,1]
	v_cvt_pk_bf16_f32 v49, v100, v101
	v_lshlrev_b32_e32 v100, 16, v50
	v_and_b32_e32 v101, 0xffff0000, v50
	v_pk_mul_f32 v[100:101], v[166:167], v[100:101] op_sel_hi:[0,1]
	v_cvt_pk_bf16_f32 v50, v100, v101
	v_lshlrev_b32_e32 v100, 16, v51
	v_and_b32_e32 v101, 0xffff0000, v51
	v_pk_mul_f32 v[166:167], v[166:167], v[100:101] op_sel_hi:[0,1]
	v_cvt_pk_bf16_f32 v51, v166, v167
	ds_write_b128 v79, v[48:51] offset:22016
	s_or_b64 exec, exec, s[66:67]
	s_and_saveexec_b64 s[24:25], s[40:41]
	s_xor_b64 s[66:67], exec, s[24:25]
	s_cbranch_execz .LBB0_917

; __device__ __forceinline__ unsigned pk2(float lo, float hi) { f32x2 v = {lo, hi}; bf16x2_t b = __builtin_convertvector(v, bf16x2_t); return __builtin_bit_cast(unsigned, b); }
; __device__ __forceinline__ float bflo(unsigned u) { return __uint_as_float(u << 16); }
; __device__ __forceinline__ float bfhi(unsigned u) { return __uint_as_float(u & 0xffff0000u); }
; template <int PASS>
; __device__ void ssd_item(const Params& p, int item, int l, unsigned char* smem) {
;     ...
;         for (int i = 0; i < 5; ++i) { const int u = tid + 256 * i, lrow = u / 40, ci = u % 40, lc = ci * 8; const u32x4 o = raw[i];
;             if (ci < 8) { *(u32x4*)(Xs + lrow * 72 + lc) = o; const float wl = s_wl[lrow];
;                 u32x4 o2; o2.x = pk2(bflo(o.x) * wl, bfhi(o.x) * wl); o2.y = pk2(bflo(o.y) * wl, bfhi(o.y) * wl); o2.z = pk2(bflo(o.z) * wl, bfhi(o.z) * wl); o2.w = pk2(bflo(o.w) * wl, bfhi(o.w) * wl);
;                 *(u32x4*)(Xws + lrow * 72 + lc) = o2; }
.LBB0_945:
	ds_write_b128 v83, v[44:47] offset:17408
	v_lshlrev_b32_e32 v50, 16, v44
	v_and_b32_e32 v51, 0xffff0000, v44
	v_pk_mul_f32 v[50:51], v[168:169], v[50:51] op_sel_hi:[0,1]
	v_cvt_pk_bf16_f32 v44, v50, v51
	v_lshlrev_b32_e32 v50, 16, v45
	v_and_b32_e32 v51, 0xffff0000, v45
	v_pk_mul_f32 v[50:51], v[168:169], v[50:51] op_sel_hi:[0,1]
	v_cvt_pk_bf16_f32 v45, v50, v51
	v_lshlrev_b32_e32 v50, 16, v46
	v_and_b32_e32 v51, 0xffff0000, v46
	v_pk_mul_f32 v[50:51], v[168:169], v[50:51] op_sel_hi:[0,1]
	v_cvt_pk_bf16_f32 v46, v50, v51
	v_lshlrev_b32_e32 v50, 16, v47
	v_and_b32_e32 v51, 0xffff0000, v47
	v_pk_mul_f32 v[168:169], v[168:169], v[50:51] op_sel_hi:[0,1]
	v_cvt_pk_bf16_f32 v47, v168, v169
	ds_write_b128 v83, v[44:47] offset:22016
	s_or_b64 exec, exec, s[66:67]
	s_and_saveexec_b64 s[24:25], s[42:43]
	s_xor_b64 s[66:67], exec, s[24:25]
	s_cbranch_execz .LBB0_919

; __device__ __forceinline__ unsigned pk2(float lo, float hi) { f32x2 v = {lo, hi}; bf16x2_t b = __builtin_convertvector(v, bf16x2_t); return __builtin_bit_cast(unsigned, b); }
; __device__ __forceinline__ float bflo(unsigned u) { return __uint_as_float(u << 16); }
; __device__ __forceinline__ float bfhi(unsigned u) { return __uint_as_float(u & 0xffff0000u); }
; template <int PASS>
; __device__ void ssd_item(const Params& p, int item, int l, unsigned char* smem) {
;     ...
;         for (int i = 0; i < 5; ++i) { const int u = tid + 256 * i, lrow = u / 40, ci = u % 40, lc = ci * 8; const u32x4 o = raw[i];
;             if (ci < 8) { *(u32x4*)(Xs + lrow * 72 + lc) = o; const float wl = s_wl[lrow];
;                 u32x4 o2; o2.x = pk2(bflo(o.x) * wl, bfhi(o.x) * wl); o2.y = pk2(bflo(o.y) * wl, bfhi(o.y) * wl); o2.z = pk2(bflo(o.z) * wl, bfhi(o.z) * wl); o2.w = pk2(bflo(o.w) * wl, bfhi(o.w) * wl);
;                 *(u32x4*)(Xws + lrow * 72 + lc) = o2; }
.LBB0_951:
	ds_write_b128 v86, v[40:43] offset:17408
	v_lshlrev_b32_e32 v46, 16, v40
	v_and_b32_e32 v47, 0xffff0000, v40
	v_pk_mul_f32 v[46:47], v[170:171], v[46:47] op_sel_hi:[0,1]
	v_cvt_pk_bf16_f32 v40, v46, v47
	v_lshlrev_b32_e32 v46, 16, v41
	v_and_b32_e32 v47, 0xffff0000, v41
	v_pk_mul_f32 v[46:47], v[170:171], v[46:47] op_sel_hi:[0,1]
	v_cvt_pk_bf16_f32 v41, v46, v47
	v_lshlrev_b32_e32 v46, 16, v42
	v_and_b32_e32 v47, 0xffff0000, v42
	v_pk_mul_f32 v[46:47], v[170:171], v[46:47] op_sel_hi:[0,1]
	v_cvt_pk_bf16_f32 v42, v46, v47
	v_lshlrev_b32_e32 v46, 16, v43
	v_and_b32_e32 v47, 0xffff0000, v43
	v_pk_mul_f32 v[170:171], v[170:171], v[46:47] op_sel_hi:[0,1]
	v_cvt_pk_bf16_f32 v43, v170, v171
	ds_write_b128 v86, v[40:43] offset:22016
	s_or_b64 exec, exec, s[66:67]
	s_and_saveexec_b64 s[24:25], s[44:45]
	s_xor_b64 s[66:67], exec, s[24:25]
	s_cbranch_execz .LBB0_921

; __device__ __forceinline__ unsigned pk2(float lo, float hi) { f32x2 v = {lo, hi}; bf16x2_t b = __builtin_convertvector(v, bf16x2_t); return __builtin_bit_cast(unsigned, b); }
; __device__ __forceinline__ float bflo(unsigned u) { return __uint_as_float(u << 16); }
; __device__ __forceinline__ float bfhi(unsigned u) { return __uint_as_float(u & 0xffff0000u); }
; template <int PASS>
; __device__ void ssd_item(const Params& p, int item, int l, unsigned char* smem) {
;     ...
;         for (int i = 0; i < 5; ++i) { const int u = tid + 256 * i, lrow = u / 40, ci = u % 40, lc = ci * 8; const u32x4 o = raw[i];
;             if (ci < 8) { *(u32x4*)(Xs + lrow * 72 + lc) = o; const float wl = s_wl[lrow];
;                 u32x4 o2; o2.x = pk2(bflo(o.x) * wl, bfhi(o.x) * wl); o2.y = pk2(bflo(o.y) * wl, bfhi(o.y) * wl); o2.z = pk2(bflo(o.z) * wl, bfhi(o.z) * wl); o2.w = pk2(bflo(o.w) * wl, bfhi(o.w) * wl);
;                 *(u32x4*)(Xws + lrow * 72 + lc) = o2; }
.LBB0_957:
	ds_write_b128 v89, v[36:39] offset:17408
	v_lshlrev_b32_e32 v42, 16, v36
	v_and_b32_e32 v43, 0xffff0000, v36
	v_pk_mul_f32 v[42:43], v[172:173], v[42:43] op_sel_hi:[0,1]
	v_cvt_pk_bf16_f32 v36, v42, v43
	v_lshlrev_b32_e32 v42, 16, v37
	v_and_b32_e32 v43, 0xffff0000, v37
	v_pk_mul_f32 v[42:43], v[172:173], v[42:43] op_sel_hi:[0,1]
	v_cvt_pk_bf16_f32 v37, v42, v43
	v_lshlrev_b32_e32 v42, 16, v38
	v_and_b32_e32 v43, 0xffff0000, v38
	v_pk_mul_f32 v[42:43], v[172:173], v[42:43] op_sel_hi:[0,1]
	v_cvt_pk_bf16_f32 v38, v42, v43
	v_lshlrev_b32_e32 v42, 16, v39
	v_and_b32_e32 v43, 0xffff0000, v39
	v_pk_mul_f32 v[172:173], v[172:173], v[42:43] op_sel_hi:[0,1]
	v_cvt_pk_bf16_f32 v39, v172, v173
	ds_write_b128 v89, v[36:39] offset:22016
	s_or_b64 exec, exec, s[66:67]
	s_and_saveexec_b64 s[24:25], s[46:47]
	s_xor_b64 s[66:67], exec, s[24:25]
	s_cbranch_execz .LBB0_923

; template <int PASS>
; __device__ void ssd_item(const Params& p, int item, int l, unsigned char* smem) {
;     ...
;                     const int jj = 16 * jt + 4 * kq + rg;
;                     const bool ok = dir ? (jj >= ii) : (jj <= ii);
;                     const float e = __expf(ci_ - s_c[jj]) * s_dt[jj];
;                     gv[rg] = ok ? cb[rg] * e : 0.f;
.LBB0_963:
	v_sub_f32_e32 v38, v37, v174
	v_mul_f32_e32 v38, 0x3fb8aa3b, v38
	v_exp_f32_e32 v38, v38
	s_nop 0
	v_mul_f32_e32 v38, v175, v38
	v_mul_f32_e32 v38, v32, v38
	s_or_b64 exec, exec, s[66:67]
	v_mov_b32_e32 v32, 0
	s_and_saveexec_b64 s[66:67], s[60:61]
	s_cbranch_execz .LBB0_927
.LBB0_964:
	v_sub_f32_e32 v32, v37, v176
	v_mul_f32_e32 v32, 0x3fb8aa3b, v32
	v_exp_f32_e32 v32, v32
	s_nop 0
	v_mul_f32_e32 v32, v177, v32
	v_mul_f32_e32 v32, v33, v32
	s_or_b64 exec, exec, s[66:67]
	s_and_saveexec_b64 s[66:67], s[62:63]
	s_cbranch_execz .LBB0_928
.LBB0_965:
	v_sub_f32_e32 v33, v37, v180
	v_mul_f32_e32 v33, 0x3fb8aa3b, v33
	v_exp_f32_e32 v33, v33
	s_nop 0
	v_mul_f32_e32 v33, v181, v33
	v_mul_f32_e32 v36, v34, v33
	s_or_b64 exec, exec, s[66:67]
	v_mov_b32_e32 v33, 0
	s_and_saveexec_b64 s[66:67], s[64:65]
	s_cbranch_execnz .LBB0_929
	s_branch .LBB0_930
